# write-through stores for the in-projection outputs only (Z is consumed cross-XCD by the mixers)
# baseline (speedup 1.0000x reference)
; __device__ __forceinline__ unsigned cvt_pk_bf16(float lo, float hi) { unsigned r; asm volatile("v_cvt_pk_bf16_f32 %0, %1, %2" : "=v"(r) : "v"(lo), "v"(hi)); return r; }
;     __device__ __forceinline__ void operator()(const f32x4 (&acc)[2][2][4][2], const Unit& u, int wr, int wc, int fr, int fq) const {
;     ...
;             for (int m = 0; m < 4; ++m) rsv[ai][m] = __builtin_amdgcn_rsqf(rsv[ai][m] * (1.0f / 1024.0f) + RMS_EPS);
; #pragma unroll
;         for (int ai = 0; ai < 2; ++ai)
; #pragma unroll
;             for (int m = 0; m < 4; ++m) {
;                 const int row = row0 + ai * HALF + m * 16;
;                 const float rs = rsv[ai][m];
;                 bf16_t* rowp = O + (size_t)row * 1536;
;                 const f32x4 a0 = acc[ai][0][m][0] * rs, a1 = acc[ai][0][m][1] * rs, b0 = acc[ai][1][m][0] * rs, b1 = acc[ai][1][m][1] * rs;
;                 if (u.pn < 2) {
;                     u32x4 w; w.x = cvt_pk_bf16(a0[0], a0[1]); w.y = cvt_pk_bf16(a0[2], a0[3]); w.z = cvt_pk_bf16(a1[0], a1[1]); w.w = cvt_pk_bf16(a1[2], a1[3]);
;                     *(u32x4*)(rowp + u.pn * 256 + wcol) = w;
;                     w.x = cvt_pk_bf16(b0[0], b0[1]); w.y = cvt_pk_bf16(b0[2], b0[3]); w.z = cvt_pk_bf16(b1[0], b1[1]); w.w = cvt_pk_bf16(b1[2], b1[3]);
;                     *(u32x4*)(rowp + u.pn * 256 + 128 + wcol) = w;
;                 } else {
;                     f32x4 r0, r1;
;                     if (u.pn < 6) { r0 = a0 * b0; r1 = a1 * b1; }
;                     else {
; #pragma unroll
;                         for (int j = 0; j < 4; ++j) { r0[j] = a0[j] * __builtin_amdgcn_rcpf(1.0f + __expf(-b0[j])); r1[j] = a1[j] * __builtin_amdgcn_rcpf(1.0f + __expf(-b1[j])); }
;                     }
;                     u32x4 w; w.x = cvt_pk_bf16(r0[0], r0[1]); w.y = cvt_pk_bf16(r0[2], r0[3]); w.z = cvt_pk_bf16(r1[0], r1[1]); w.w = cvt_pk_bf16(r1[2], r1[3]);
;                     *(u32x4*)(rowp + (u.pn < 6 ? 512 + (u.pn - 2) * 128 : 1024 + (u.pn - 6) * 128) + wcol) = w;
.LBB0_114:
	v_fmamk_f32 v116, v170, 0x3a800000, v164
	v_rsq_f32_e32 v118, v116
	v_lshl_add_u64 v[116:117], v[156:157], 0, v[136:137]
	v_or_b32_e32 v119, 16, v148
	global_store_dwordx4 v[116:117], v[112:115], off sc1
	v_pk_mul_f32 v[110:111], v[110:111], v[118:119] op_sel_hi:[1,0]
	v_pk_mul_f32 v[116:117], v[108:109], v[118:119] op_sel_hi:[1,0]
	v_mov_b64_e32 v[112:113], s[34:35]
	v_mad_i64_i32 v[112:113], s[0:1], v119, s64, v[112:113]
	v_pk_mul_f32 v[114:115], v[104:105], v[118:119] op_sel_hi:[1,0]
	v_pk_mul_f32 v[104:105], v[96:97], v[118:119] op_sel_hi:[1,0]
	v_cndmask_b32_e64 v96, 0, 1, s[94:95]
	v_pk_mul_f32 v[108:109], v[106:107], v[118:119] op_sel_hi:[1,0]
	v_pk_mul_f32 v[102:103], v[102:103], v[118:119] op_sel_hi:[1,0]
	v_pk_mul_f32 v[106:107], v[100:101], v[118:119] op_sel_hi:[1,0]
	v_pk_mul_f32 v[100:101], v[98:99], v[118:119] op_sel_hi:[1,0]
	v_cmp_ne_u32_e64 s[0:1], 1, v96
	s_andn2_b64 vcc, exec, s[94:95]
	s_mov_b64 s[28:29], -1
	s_cbranch_vccnz .LBB0_118
	s_cmp_lt_u32 s50, 6
	v_mov_b32_e32 v96, v106
	v_mov_b32_e32 v97, v107
	v_mov_b32_e32 v118, v102
	v_mov_b32_e32 v119, v103
	v_mov_b32_e32 v98, v104
	v_mov_b32_e32 v99, v105
	v_mov_b32_e32 v120, v100
	v_mov_b32_e32 v121, v101
	s_cbranch_scc1 .LBB0_117
	v_mul_f32_e32 v97, 0xbfb8aa3b, v104
	v_mul_f32_e32 v98, 0xbfb8aa3b, v107
	v_exp_f32_e32 v97, v97
	v_exp_f32_e32 v99, v98
	v_mul_f32_e32 v98, 0xbfb8aa3b, v105
	v_exp_f32_e32 v118, v98
	v_add_f32_e32 v97, 1.0, v97
	v_mul_f32_e32 v119, 0xbfb8aa3b, v100
	v_mul_f32_e32 v120, 0xbfb8aa3b, v103
	v_mul_f32_e32 v96, 0xbfb8aa3b, v106
	v_rcp_f32_e32 v98, v97
	v_add_f32_e32 v97, 1.0, v99
	v_add_f32_e32 v99, 1.0, v118
	v_mul_f32_e32 v118, 0xbfb8aa3b, v102
	v_exp_f32_e32 v119, v119
	v_exp_f32_e32 v121, v120
	v_mul_f32_e32 v120, 0xbfb8aa3b, v101
	v_exp_f32_e32 v96, v96
	v_exp_f32_e32 v118, v118
	v_exp_f32_e32 v122, v120
	v_add_f32_e32 v119, 1.0, v119
	v_add_f32_e32 v96, 1.0, v96
	v_add_f32_e32 v118, 1.0, v118
	v_rcp_f32_e32 v120, v119
	v_add_f32_e32 v119, 1.0, v121
	v_add_f32_e32 v121, 1.0, v122
	v_rcp_f32_e32 v96, v96
	v_rcp_f32_e32 v97, v97
	v_rcp_f32_e32 v99, v99
	v_rcp_f32_e32 v118, v118
	v_rcp_f32_e32 v119, v119
	v_rcp_f32_e32 v121, v121

; __device__ __forceinline__ unsigned cvt_pk_bf16(float lo, float hi) { unsigned r; asm volatile("v_cvt_pk_bf16_f32 %0, %1, %2" : "=v"(r) : "v"(lo), "v"(hi)); return r; }
;     __device__ __forceinline__ void operator()(const f32x4 (&acc)[2][2][4][2], const Unit& u, int wr, int wc, int fr, int fq) const {
;     ...
;             for (int m = 0; m < 4; ++m) rsv[ai][m] = __builtin_amdgcn_rsqf(rsv[ai][m] * (1.0f / 1024.0f) + RMS_EPS);
; #pragma unroll
;         for (int ai = 0; ai < 2; ++ai)
; #pragma unroll
;             for (int m = 0; m < 4; ++m) {
;                 const int row = row0 + ai * HALF + m * 16;
;                 const float rs = rsv[ai][m];
;                 bf16_t* rowp = O + (size_t)row * 1536;
;                 const f32x4 a0 = acc[ai][0][m][0] * rs, a1 = acc[ai][0][m][1] * rs, b0 = acc[ai][1][m][0] * rs, b1 = acc[ai][1][m][1] * rs;
;                 if (u.pn < 2) {
;                     u32x4 w; w.x = cvt_pk_bf16(a0[0], a0[1]); w.y = cvt_pk_bf16(a0[2], a0[3]); w.z = cvt_pk_bf16(a1[0], a1[1]); w.w = cvt_pk_bf16(a1[2], a1[3]);
;                     *(u32x4*)(rowp + u.pn * 256 + wcol) = w;
;                     w.x = cvt_pk_bf16(b0[0], b0[1]); w.y = cvt_pk_bf16(b0[2], b0[3]); w.z = cvt_pk_bf16(b1[0], b1[1]); w.w = cvt_pk_bf16(b1[2], b1[3]);
;                     *(u32x4*)(rowp + u.pn * 256 + 128 + wcol) = w;
;                 } else {
;                     f32x4 r0, r1;
;                     if (u.pn < 6) { r0 = a0 * b0; r1 = a1 * b1; }
;                     else {
; #pragma unroll
;                         for (int j = 0; j < 4; ++j) { r0[j] = a0[j] * __builtin_amdgcn_rcpf(1.0f + __expf(-b0[j])); r1[j] = a1[j] * __builtin_amdgcn_rcpf(1.0f + __expf(-b1[j])); }
;                     }
;                     u32x4 w; w.x = cvt_pk_bf16(r0[0], r0[1]); w.y = cvt_pk_bf16(r0[2], r0[3]); w.z = cvt_pk_bf16(r1[0], r1[1]); w.w = cvt_pk_bf16(r1[2], r1[3]);
;                     *(u32x4*)(rowp + (u.pn < 6 ? 512 + (u.pn - 2) * 128 : 1024 + (u.pn - 6) * 128) + wcol) = w;
.LBB0_120:
	v_fmamk_f32 v100, v169, 0x3a800000, v164
	v_rsq_f32_e32 v102, v100
	v_lshl_add_u64 v[100:101], v[118:119], 0, v[136:137]
	v_or_b32_e32 v103, 32, v148
	global_store_dwordx4 v[100:101], v[96:99], off sc1
	v_pk_mul_f32 v[94:95], v[94:95], v[102:103] op_sel_hi:[1,0]
	v_pk_mul_f32 v[100:101], v[92:93], v[102:103] op_sel_hi:[1,0]
	v_mov_b64_e32 v[96:97], s[34:35]
	v_mad_i64_i32 v[96:97], s[12:13], v103, s64, v[96:97]
	v_pk_mul_f32 v[92:93], v[90:91], v[102:103] op_sel_hi:[1,0]
	v_pk_mul_f32 v[98:99], v[88:89], v[102:103] op_sel_hi:[1,0]
	v_pk_mul_f32 v[86:87], v[86:87], v[102:103] op_sel_hi:[1,0]
	v_pk_mul_f32 v[90:91], v[84:85], v[102:103] op_sel_hi:[1,0]
	v_pk_mul_f32 v[84:85], v[82:83], v[102:103] op_sel_hi:[1,0]
	v_pk_mul_f32 v[88:89], v[80:81], v[102:103] op_sel_hi:[1,0]
	s_and_b64 vcc, exec, s[0:1]
	s_mov_b64 s[28:29], -1
	s_cbranch_vccnz .LBB0_124
	s_cmp_lt_u32 s50, 6
	v_mov_b32_e32 v80, v90
	v_mov_b32_e32 v81, v91
	v_mov_b32_e32 v102, v86
	v_mov_b32_e32 v103, v87
	v_mov_b32_e32 v82, v88
	v_mov_b32_e32 v83, v89
	v_mov_b32_e32 v104, v84
	v_mov_b32_e32 v105, v85
	s_cbranch_scc1 .LBB0_123
	v_mul_f32_e32 v81, 0xbfb8aa3b, v88
	v_mul_f32_e32 v82, 0xbfb8aa3b, v91
	v_exp_f32_e32 v81, v81
	v_exp_f32_e32 v83, v82
	v_mul_f32_e32 v82, 0xbfb8aa3b, v89
	v_exp_f32_e32 v102, v82
	v_add_f32_e32 v81, 1.0, v81
	v_mul_f32_e32 v103, 0xbfb8aa3b, v84
	v_mul_f32_e32 v104, 0xbfb8aa3b, v87
	v_mul_f32_e32 v80, 0xbfb8aa3b, v90
	v_rcp_f32_e32 v82, v81
	v_add_f32_e32 v81, 1.0, v83
	v_add_f32_e32 v83, 1.0, v102
	v_mul_f32_e32 v102, 0xbfb8aa3b, v86
	v_exp_f32_e32 v103, v103
	v_exp_f32_e32 v105, v104
	v_mul_f32_e32 v104, 0xbfb8aa3b, v85
	v_exp_f32_e32 v80, v80
	v_exp_f32_e32 v102, v102
	v_exp_f32_e32 v106, v104
	v_add_f32_e32 v103, 1.0, v103
	v_add_f32_e32 v80, 1.0, v80
	v_add_f32_e32 v102, 1.0, v102
	v_rcp_f32_e32 v104, v103
	v_add_f32_e32 v103, 1.0, v105
	v_add_f32_e32 v105, 1.0, v106
	v_rcp_f32_e32 v80, v80
	v_rcp_f32_e32 v81, v81
	v_rcp_f32_e32 v83, v83
	v_rcp_f32_e32 v102, v102
	v_rcp_f32_e32 v103, v103
	v_rcp_f32_e32 v105, v105

; __device__ __forceinline__ unsigned cvt_pk_bf16(float lo, float hi) { unsigned r; asm volatile("v_cvt_pk_bf16_f32 %0, %1, %2" : "=v"(r) : "v"(lo), "v"(hi)); return r; }
;     __device__ __forceinline__ void operator()(const f32x4 (&acc)[2][2][4][2], const Unit& u, int wr, int wc, int fr, int fq) const {
;     ...
;             for (int m = 0; m < 4; ++m) rsv[ai][m] = __builtin_amdgcn_rsqf(rsv[ai][m] * (1.0f / 1024.0f) + RMS_EPS);
; #pragma unroll
;         for (int ai = 0; ai < 2; ++ai)
; #pragma unroll
;             for (int m = 0; m < 4; ++m) {
;                 const int row = row0 + ai * HALF + m * 16;
;                 const float rs = rsv[ai][m];
;                 bf16_t* rowp = O + (size_t)row * 1536;
;                 const f32x4 a0 = acc[ai][0][m][0] * rs, a1 = acc[ai][0][m][1] * rs, b0 = acc[ai][1][m][0] * rs, b1 = acc[ai][1][m][1] * rs;
;                 if (u.pn < 2) {
;                     u32x4 w; w.x = cvt_pk_bf16(a0[0], a0[1]); w.y = cvt_pk_bf16(a0[2], a0[3]); w.z = cvt_pk_bf16(a1[0], a1[1]); w.w = cvt_pk_bf16(a1[2], a1[3]);
;                     *(u32x4*)(rowp + u.pn * 256 + wcol) = w;
;                     w.x = cvt_pk_bf16(b0[0], b0[1]); w.y = cvt_pk_bf16(b0[2], b0[3]); w.z = cvt_pk_bf16(b1[0], b1[1]); w.w = cvt_pk_bf16(b1[2], b1[3]);
;                     *(u32x4*)(rowp + u.pn * 256 + 128 + wcol) = w;
;                 } else {
;                     f32x4 r0, r1;
;                     if (u.pn < 6) { r0 = a0 * b0; r1 = a1 * b1; }
;                     else {
; #pragma unroll
;                         for (int j = 0; j < 4; ++j) { r0[j] = a0[j] * __builtin_amdgcn_rcpf(1.0f + __expf(-b0[j])); r1[j] = a1[j] * __builtin_amdgcn_rcpf(1.0f + __expf(-b1[j])); }
;                     }
;                     u32x4 w; w.x = cvt_pk_bf16(r0[0], r0[1]); w.y = cvt_pk_bf16(r0[2], r0[3]); w.z = cvt_pk_bf16(r1[0], r1[1]); w.w = cvt_pk_bf16(r1[2], r1[3]);
;                     *(u32x4*)(rowp + (u.pn < 6 ? 512 + (u.pn - 2) * 128 : 1024 + (u.pn - 6) * 128) + wcol) = w;
.LBB0_126:
	v_fmamk_f32 v84, v168, 0x3a800000, v164
	v_rsq_f32_e32 v86, v84
	v_lshl_add_u64 v[84:85], v[102:103], 0, v[136:137]
	v_or_b32_e32 v87, 48, v148
	global_store_dwordx4 v[84:85], v[80:83], off sc1
	v_pk_mul_f32 v[78:79], v[78:79], v[86:87] op_sel_hi:[1,0]
	v_pk_mul_f32 v[84:85], v[76:77], v[86:87] op_sel_hi:[1,0]
	v_mov_b64_e32 v[80:81], s[34:35]
	v_mad_i64_i32 v[80:81], s[12:13], v87, s64, v[80:81]
	v_pk_mul_f32 v[76:77], v[74:75], v[86:87] op_sel_hi:[1,0]
	v_pk_mul_f32 v[82:83], v[72:73], v[86:87] op_sel_hi:[1,0]
	v_pk_mul_f32 v[70:71], v[70:71], v[86:87] op_sel_hi:[1,0]
	v_pk_mul_f32 v[74:75], v[68:69], v[86:87] op_sel_hi:[1,0]
	v_pk_mul_f32 v[68:69], v[66:67], v[86:87] op_sel_hi:[1,0]
	v_pk_mul_f32 v[72:73], v[64:65], v[86:87] op_sel_hi:[1,0]
	s_and_b64 vcc, exec, s[0:1]
	s_mov_b64 s[28:29], -1
	s_cbranch_vccnz .LBB0_130
	s_cmp_lt_u32 s50, 6
	v_mov_b32_e32 v64, v74
	v_mov_b32_e32 v65, v75
	v_mov_b32_e32 v86, v70
	v_mov_b32_e32 v87, v71
	v_mov_b32_e32 v66, v72
	v_mov_b32_e32 v67, v73
	v_mov_b32_e32 v88, v68
	v_mov_b32_e32 v89, v69
	s_cbranch_scc1 .LBB0_129
	v_mul_f32_e32 v65, 0xbfb8aa3b, v72
	v_mul_f32_e32 v66, 0xbfb8aa3b, v75
	v_exp_f32_e32 v65, v65
	v_exp_f32_e32 v67, v66
	v_mul_f32_e32 v66, 0xbfb8aa3b, v73
	v_exp_f32_e32 v86, v66
	v_add_f32_e32 v65, 1.0, v65
	v_mul_f32_e32 v87, 0xbfb8aa3b, v68
	v_mul_f32_e32 v88, 0xbfb8aa3b, v71
	v_mul_f32_e32 v64, 0xbfb8aa3b, v74
	v_rcp_f32_e32 v66, v65
	v_add_f32_e32 v65, 1.0, v67
	v_add_f32_e32 v67, 1.0, v86
	v_mul_f32_e32 v86, 0xbfb8aa3b, v70
	v_exp_f32_e32 v87, v87
	v_exp_f32_e32 v89, v88
	v_mul_f32_e32 v88, 0xbfb8aa3b, v69
	v_exp_f32_e32 v64, v64
	v_exp_f32_e32 v86, v86
	v_exp_f32_e32 v90, v88
	v_add_f32_e32 v87, 1.0, v87
	v_add_f32_e32 v64, 1.0, v64
	v_add_f32_e32 v86, 1.0, v86
	v_rcp_f32_e32 v88, v87
	v_add_f32_e32 v87, 1.0, v89
	v_add_f32_e32 v89, 1.0, v90
	v_rcp_f32_e32 v64, v64
	v_rcp_f32_e32 v65, v65
	v_rcp_f32_e32 v67, v67
	v_rcp_f32_e32 v86, v86
	v_rcp_f32_e32 v87, v87
	v_rcp_f32_e32 v89, v89

; __device__ __forceinline__ unsigned cvt_pk_bf16(float lo, float hi) { unsigned r; asm volatile("v_cvt_pk_bf16_f32 %0, %1, %2" : "=v"(r) : "v"(lo), "v"(hi)); return r; }
;     __device__ __forceinline__ void operator()(const f32x4 (&acc)[2][2][4][2], const Unit& u, int wr, int wc, int fr, int fq) const {
;     ...
;             for (int m = 0; m < 4; ++m) rsv[ai][m] = __builtin_amdgcn_rsqf(rsv[ai][m] * (1.0f / 1024.0f) + RMS_EPS);
; #pragma unroll
;         for (int ai = 0; ai < 2; ++ai)
; #pragma unroll
;             for (int m = 0; m < 4; ++m) {
;                 const int row = row0 + ai * HALF + m * 16;
;                 const float rs = rsv[ai][m];
;                 bf16_t* rowp = O + (size_t)row * 1536;
;                 const f32x4 a0 = acc[ai][0][m][0] * rs, a1 = acc[ai][0][m][1] * rs, b0 = acc[ai][1][m][0] * rs, b1 = acc[ai][1][m][1] * rs;
;                 if (u.pn < 2) {
;                     u32x4 w; w.x = cvt_pk_bf16(a0[0], a0[1]); w.y = cvt_pk_bf16(a0[2], a0[3]); w.z = cvt_pk_bf16(a1[0], a1[1]); w.w = cvt_pk_bf16(a1[2], a1[3]);
;                     *(u32x4*)(rowp + u.pn * 256 + wcol) = w;
;                     w.x = cvt_pk_bf16(b0[0], b0[1]); w.y = cvt_pk_bf16(b0[2], b0[3]); w.z = cvt_pk_bf16(b1[0], b1[1]); w.w = cvt_pk_bf16(b1[2], b1[3]);
;                     *(u32x4*)(rowp + u.pn * 256 + 128 + wcol) = w;
;                 } else {
;                     f32x4 r0, r1;
;                     if (u.pn < 6) { r0 = a0 * b0; r1 = a1 * b1; }
;                     else {
; #pragma unroll
;                         for (int j = 0; j < 4; ++j) { r0[j] = a0[j] * __builtin_amdgcn_rcpf(1.0f + __expf(-b0[j])); r1[j] = a1[j] * __builtin_amdgcn_rcpf(1.0f + __expf(-b1[j])); }
;                     }
;                     u32x4 w; w.x = cvt_pk_bf16(r0[0], r0[1]); w.y = cvt_pk_bf16(r0[2], r0[3]); w.z = cvt_pk_bf16(r1[0], r1[1]); w.w = cvt_pk_bf16(r1[2], r1[3]);
;                     *(u32x4*)(rowp + (u.pn < 6 ? 512 + (u.pn - 2) * 128 : 1024 + (u.pn - 6) * 128) + wcol) = w;
.LBB0_132:
	v_fmamk_f32 v68, v167, 0x3a800000, v164
	v_rsq_f32_e32 v70, v68
	v_lshl_add_u64 v[68:69], v[86:87], 0, v[136:137]
	v_add_u32_e32 v71, 0x80, v148
	global_store_dwordx4 v[68:69], v[64:67], off sc1
	v_pk_mul_f32 v[62:63], v[62:63], v[70:71] op_sel_hi:[1,0]
	v_pk_mul_f32 v[68:69], v[60:61], v[70:71] op_sel_hi:[1,0]
	v_mov_b64_e32 v[64:65], s[34:35]
	v_mad_i64_i32 v[64:65], s[12:13], v71, s64, v[64:65]
	v_pk_mul_f32 v[60:61], v[58:59], v[70:71] op_sel_hi:[1,0]
	v_pk_mul_f32 v[66:67], v[56:57], v[70:71] op_sel_hi:[1,0]
	v_pk_mul_f32 v[54:55], v[54:55], v[70:71] op_sel_hi:[1,0]
	v_pk_mul_f32 v[58:59], v[52:53], v[70:71] op_sel_hi:[1,0]
	v_pk_mul_f32 v[52:53], v[50:51], v[70:71] op_sel_hi:[1,0]
	v_pk_mul_f32 v[56:57], v[48:49], v[70:71] op_sel_hi:[1,0]
	s_and_b64 vcc, exec, s[0:1]
	s_mov_b64 s[28:29], -1
	s_cbranch_vccnz .LBB0_136
	s_cmp_lt_u32 s50, 6
	v_mov_b32_e32 v48, v58
	v_mov_b32_e32 v49, v59
	v_mov_b32_e32 v70, v54
	v_mov_b32_e32 v71, v55
	v_mov_b32_e32 v50, v56
	v_mov_b32_e32 v51, v57
	v_mov_b32_e32 v72, v52
	v_mov_b32_e32 v73, v53
	s_cbranch_scc1 .LBB0_135
	v_mul_f32_e32 v49, 0xbfb8aa3b, v56
	v_mul_f32_e32 v50, 0xbfb8aa3b, v59
	v_exp_f32_e32 v49, v49
	v_exp_f32_e32 v51, v50
	v_mul_f32_e32 v50, 0xbfb8aa3b, v57
	v_exp_f32_e32 v70, v50
	v_add_f32_e32 v49, 1.0, v49
	v_mul_f32_e32 v71, 0xbfb8aa3b, v52
	v_mul_f32_e32 v72, 0xbfb8aa3b, v55
	v_mul_f32_e32 v48, 0xbfb8aa3b, v58
	v_rcp_f32_e32 v50, v49
	v_add_f32_e32 v49, 1.0, v51
	v_add_f32_e32 v51, 1.0, v70
	v_mul_f32_e32 v70, 0xbfb8aa3b, v54
	v_exp_f32_e32 v71, v71
	v_exp_f32_e32 v73, v72
	v_mul_f32_e32 v72, 0xbfb8aa3b, v53
	v_exp_f32_e32 v48, v48
	v_exp_f32_e32 v70, v70
	v_exp_f32_e32 v74, v72
	v_add_f32_e32 v71, 1.0, v71
	v_add_f32_e32 v48, 1.0, v48
	v_add_f32_e32 v70, 1.0, v70
	v_rcp_f32_e32 v72, v71
	v_add_f32_e32 v71, 1.0, v73
	v_add_f32_e32 v73, 1.0, v74
	v_rcp_f32_e32 v48, v48
	v_rcp_f32_e32 v49, v49
	v_rcp_f32_e32 v51, v51
	v_rcp_f32_e32 v70, v70
	v_rcp_f32_e32 v71, v71
	v_rcp_f32_e32 v73, v73

; __device__ __forceinline__ unsigned cvt_pk_bf16(float lo, float hi) { unsigned r; asm volatile("v_cvt_pk_bf16_f32 %0, %1, %2" : "=v"(r) : "v"(lo), "v"(hi)); return r; }
;     __device__ __forceinline__ void operator()(const f32x4 (&acc)[2][2][4][2], const Unit& u, int wr, int wc, int fr, int fq) const {
;     ...
;             for (int m = 0; m < 4; ++m) rsv[ai][m] = __builtin_amdgcn_rsqf(rsv[ai][m] * (1.0f / 1024.0f) + RMS_EPS);
; #pragma unroll
;         for (int ai = 0; ai < 2; ++ai)
; #pragma unroll
;             for (int m = 0; m < 4; ++m) {
;                 const int row = row0 + ai * HALF + m * 16;
;                 const float rs = rsv[ai][m];
;                 bf16_t* rowp = O + (size_t)row * 1536;
;                 const f32x4 a0 = acc[ai][0][m][0] * rs, a1 = acc[ai][0][m][1] * rs, b0 = acc[ai][1][m][0] * rs, b1 = acc[ai][1][m][1] * rs;
;                 if (u.pn < 2) {
;                     u32x4 w; w.x = cvt_pk_bf16(a0[0], a0[1]); w.y = cvt_pk_bf16(a0[2], a0[3]); w.z = cvt_pk_bf16(a1[0], a1[1]); w.w = cvt_pk_bf16(a1[2], a1[3]);
;                     *(u32x4*)(rowp + u.pn * 256 + wcol) = w;
;                     w.x = cvt_pk_bf16(b0[0], b0[1]); w.y = cvt_pk_bf16(b0[2], b0[3]); w.z = cvt_pk_bf16(b1[0], b1[1]); w.w = cvt_pk_bf16(b1[2], b1[3]);
;                     *(u32x4*)(rowp + u.pn * 256 + 128 + wcol) = w;
;                 } else {
;                     f32x4 r0, r1;
;                     if (u.pn < 6) { r0 = a0 * b0; r1 = a1 * b1; }
;                     else {
; #pragma unroll
;                         for (int j = 0; j < 4; ++j) { r0[j] = a0[j] * __builtin_amdgcn_rcpf(1.0f + __expf(-b0[j])); r1[j] = a1[j] * __builtin_amdgcn_rcpf(1.0f + __expf(-b1[j])); }
;                     }
;                     u32x4 w; w.x = cvt_pk_bf16(r0[0], r0[1]); w.y = cvt_pk_bf16(r0[2], r0[3]); w.z = cvt_pk_bf16(r1[0], r1[1]); w.w = cvt_pk_bf16(r1[2], r1[3]);
;                     *(u32x4*)(rowp + (u.pn < 6 ? 512 + (u.pn - 2) * 128 : 1024 + (u.pn - 6) * 128) + wcol) = w;
.LBB0_138:
	v_fmamk_f32 v52, v166, 0x3a800000, v164
	v_rsq_f32_e32 v54, v52
	v_lshl_add_u64 v[52:53], v[70:71], 0, v[136:137]
	v_add_u32_e32 v55, 0x90, v148
	global_store_dwordx4 v[52:53], v[48:51], off sc1
	v_pk_mul_f32 v[46:47], v[46:47], v[54:55] op_sel_hi:[1,0]
	v_pk_mul_f32 v[52:53], v[44:45], v[54:55] op_sel_hi:[1,0]
	v_mov_b64_e32 v[48:49], s[34:35]
	v_mad_i64_i32 v[48:49], s[12:13], v55, s64, v[48:49]
	v_pk_mul_f32 v[44:45], v[42:43], v[54:55] op_sel_hi:[1,0]
	v_pk_mul_f32 v[50:51], v[40:41], v[54:55] op_sel_hi:[1,0]
	v_pk_mul_f32 v[38:39], v[38:39], v[54:55] op_sel_hi:[1,0]
	v_pk_mul_f32 v[42:43], v[36:37], v[54:55] op_sel_hi:[1,0]
	v_pk_mul_f32 v[36:37], v[34:35], v[54:55] op_sel_hi:[1,0]
	v_pk_mul_f32 v[40:41], v[32:33], v[54:55] op_sel_hi:[1,0]
	s_and_b64 vcc, exec, s[0:1]
	s_mov_b64 s[28:29], -1
	s_cbranch_vccnz .LBB0_142
	s_cmp_lt_u32 s50, 6
	v_mov_b32_e32 v32, v42
	v_mov_b32_e32 v33, v43
	v_mov_b32_e32 v54, v38
	v_mov_b32_e32 v55, v39
	v_mov_b32_e32 v34, v40
	v_mov_b32_e32 v35, v41
	v_mov_b32_e32 v56, v36
	v_mov_b32_e32 v57, v37
	s_cbranch_scc1 .LBB0_141
	v_mul_f32_e32 v33, 0xbfb8aa3b, v40
	v_mul_f32_e32 v34, 0xbfb8aa3b, v43
	v_exp_f32_e32 v33, v33
	v_exp_f32_e32 v35, v34
	v_mul_f32_e32 v34, 0xbfb8aa3b, v41
	v_exp_f32_e32 v54, v34
	v_add_f32_e32 v33, 1.0, v33
	v_mul_f32_e32 v55, 0xbfb8aa3b, v36
	v_mul_f32_e32 v56, 0xbfb8aa3b, v39
	v_mul_f32_e32 v32, 0xbfb8aa3b, v42
	v_rcp_f32_e32 v34, v33
	v_add_f32_e32 v33, 1.0, v35
	v_add_f32_e32 v35, 1.0, v54
	v_mul_f32_e32 v54, 0xbfb8aa3b, v38
	v_exp_f32_e32 v55, v55
	v_exp_f32_e32 v57, v56
	v_mul_f32_e32 v56, 0xbfb8aa3b, v37
	v_exp_f32_e32 v32, v32
	v_exp_f32_e32 v54, v54
	v_exp_f32_e32 v58, v56
	v_add_f32_e32 v55, 1.0, v55
	v_add_f32_e32 v32, 1.0, v32
	v_add_f32_e32 v54, 1.0, v54
	v_rcp_f32_e32 v56, v55
	v_add_f32_e32 v55, 1.0, v57
	v_add_f32_e32 v57, 1.0, v58
	v_rcp_f32_e32 v32, v32
	v_rcp_f32_e32 v33, v33
	v_rcp_f32_e32 v35, v35
	v_rcp_f32_e32 v54, v54
	v_rcp_f32_e32 v55, v55
	v_rcp_f32_e32 v57, v57

; __device__ __forceinline__ unsigned cvt_pk_bf16(float lo, float hi) { unsigned r; asm volatile("v_cvt_pk_bf16_f32 %0, %1, %2" : "=v"(r) : "v"(lo), "v"(hi)); return r; }
;     __device__ __forceinline__ void operator()(const f32x4 (&acc)[2][2][4][2], const Unit& u, int wr, int wc, int fr, int fq) const {
;     ...
;             for (int m = 0; m < 4; ++m) rsv[ai][m] = __builtin_amdgcn_rsqf(rsv[ai][m] * (1.0f / 1024.0f) + RMS_EPS);
; #pragma unroll
;         for (int ai = 0; ai < 2; ++ai)
; #pragma unroll
;             for (int m = 0; m < 4; ++m) {
;                 const int row = row0 + ai * HALF + m * 16;
;                 const float rs = rsv[ai][m];
;                 bf16_t* rowp = O + (size_t)row * 1536;
;                 const f32x4 a0 = acc[ai][0][m][0] * rs, a1 = acc[ai][0][m][1] * rs, b0 = acc[ai][1][m][0] * rs, b1 = acc[ai][1][m][1] * rs;
;                 if (u.pn < 2) {
;                     u32x4 w; w.x = cvt_pk_bf16(a0[0], a0[1]); w.y = cvt_pk_bf16(a0[2], a0[3]); w.z = cvt_pk_bf16(a1[0], a1[1]); w.w = cvt_pk_bf16(a1[2], a1[3]);
;                     *(u32x4*)(rowp + u.pn * 256 + wcol) = w;
;                     w.x = cvt_pk_bf16(b0[0], b0[1]); w.y = cvt_pk_bf16(b0[2], b0[3]); w.z = cvt_pk_bf16(b1[0], b1[1]); w.w = cvt_pk_bf16(b1[2], b1[3]);
;                     *(u32x4*)(rowp + u.pn * 256 + 128 + wcol) = w;
;                 } else {
;                     f32x4 r0, r1;
;                     if (u.pn < 6) { r0 = a0 * b0; r1 = a1 * b1; }
;                     else {
; #pragma unroll
;                         for (int j = 0; j < 4; ++j) { r0[j] = a0[j] * __builtin_amdgcn_rcpf(1.0f + __expf(-b0[j])); r1[j] = a1[j] * __builtin_amdgcn_rcpf(1.0f + __expf(-b1[j])); }
;                     }
;                     u32x4 w; w.x = cvt_pk_bf16(r0[0], r0[1]); w.y = cvt_pk_bf16(r0[2], r0[3]); w.z = cvt_pk_bf16(r1[0], r1[1]); w.w = cvt_pk_bf16(r1[2], r1[3]);
;                     *(u32x4*)(rowp + (u.pn < 6 ? 512 + (u.pn - 2) * 128 : 1024 + (u.pn - 6) * 128) + wcol) = w;
.LBB0_144:
	v_fmamk_f32 v36, v165, 0x3a800000, v164
	v_rsq_f32_e32 v38, v36
	v_lshl_add_u64 v[36:37], v[54:55], 0, v[136:137]
	v_add_u32_e32 v39, 0xa0, v148
	global_store_dwordx4 v[36:37], v[32:35], off sc1
	v_pk_mul_f32 v[30:31], v[30:31], v[38:39] op_sel_hi:[1,0]
	v_pk_mul_f32 v[36:37], v[28:29], v[38:39] op_sel_hi:[1,0]
	v_mov_b64_e32 v[32:33], s[34:35]
	v_mad_i64_i32 v[32:33], s[12:13], v39, s64, v[32:33]
	v_pk_mul_f32 v[28:29], v[26:27], v[38:39] op_sel_hi:[1,0]
	v_pk_mul_f32 v[34:35], v[24:25], v[38:39] op_sel_hi:[1,0]
	v_pk_mul_f32 v[22:23], v[22:23], v[38:39] op_sel_hi:[1,0]
	v_pk_mul_f32 v[26:27], v[20:21], v[38:39] op_sel_hi:[1,0]
	v_pk_mul_f32 v[20:21], v[18:19], v[38:39] op_sel_hi:[1,0]
	v_pk_mul_f32 v[24:25], v[16:17], v[38:39] op_sel_hi:[1,0]
	s_and_b64 vcc, exec, s[0:1]
	s_mov_b64 s[28:29], -1
	s_cbranch_vccnz .LBB0_148
	s_cmp_lt_u32 s50, 6
	v_mov_b32_e32 v16, v26
	v_mov_b32_e32 v17, v27
	v_mov_b32_e32 v38, v22
	v_mov_b32_e32 v39, v23
	v_mov_b32_e32 v18, v24
	v_mov_b32_e32 v19, v25
	v_mov_b32_e32 v40, v20
	v_mov_b32_e32 v41, v21
	s_cbranch_scc1 .LBB0_147
	v_mul_f32_e32 v17, 0xbfb8aa3b, v24
	v_mul_f32_e32 v18, 0xbfb8aa3b, v27
	v_exp_f32_e32 v17, v17
	v_exp_f32_e32 v19, v18
	v_mul_f32_e32 v18, 0xbfb8aa3b, v25
	v_exp_f32_e32 v38, v18
	v_add_f32_e32 v17, 1.0, v17
	v_mul_f32_e32 v39, 0xbfb8aa3b, v20
	v_mul_f32_e32 v40, 0xbfb8aa3b, v23
	v_mul_f32_e32 v16, 0xbfb8aa3b, v26
	v_rcp_f32_e32 v18, v17
	v_add_f32_e32 v17, 1.0, v19
	v_add_f32_e32 v19, 1.0, v38
	v_mul_f32_e32 v38, 0xbfb8aa3b, v22
	v_exp_f32_e32 v39, v39
	v_exp_f32_e32 v41, v40
	v_mul_f32_e32 v40, 0xbfb8aa3b, v21
	v_exp_f32_e32 v16, v16
	v_exp_f32_e32 v38, v38
	v_exp_f32_e32 v42, v40
	v_add_f32_e32 v39, 1.0, v39
	v_add_f32_e32 v16, 1.0, v16
	v_add_f32_e32 v38, 1.0, v38
	v_rcp_f32_e32 v40, v39
	v_add_f32_e32 v39, 1.0, v41
	v_add_f32_e32 v41, 1.0, v42
	v_rcp_f32_e32 v16, v16
	v_rcp_f32_e32 v17, v17
	v_rcp_f32_e32 v19, v19
	v_rcp_f32_e32 v38, v38
	v_rcp_f32_e32 v39, v39
	v_rcp_f32_e32 v41, v41

; __device__ __forceinline__ unsigned cvt_pk_bf16(float lo, float hi) { unsigned r; asm volatile("v_cvt_pk_bf16_f32 %0, %1, %2" : "=v"(r) : "v"(lo), "v"(hi)); return r; }
;     __device__ __forceinline__ void operator()(const f32x4 (&acc)[2][2][4][2], const Unit& u, int wr, int wc, int fr, int fq) const {
;     ...
;             for (int m = 0; m < 4; ++m) rsv[ai][m] = __builtin_amdgcn_rsqf(rsv[ai][m] * (1.0f / 1024.0f) + RMS_EPS);
; #pragma unroll
;         for (int ai = 0; ai < 2; ++ai)
; #pragma unroll
;             for (int m = 0; m < 4; ++m) {
;                 const int row = row0 + ai * HALF + m * 16;
;                 const float rs = rsv[ai][m];
;                 bf16_t* rowp = O + (size_t)row * 1536;
;                 const f32x4 a0 = acc[ai][0][m][0] * rs, a1 = acc[ai][0][m][1] * rs, b0 = acc[ai][1][m][0] * rs, b1 = acc[ai][1][m][1] * rs;
;                 if (u.pn < 2) {
;                     u32x4 w; w.x = cvt_pk_bf16(a0[0], a0[1]); w.y = cvt_pk_bf16(a0[2], a0[3]); w.z = cvt_pk_bf16(a1[0], a1[1]); w.w = cvt_pk_bf16(a1[2], a1[3]);
;                     *(u32x4*)(rowp + u.pn * 256 + wcol) = w;
;                     w.x = cvt_pk_bf16(b0[0], b0[1]); w.y = cvt_pk_bf16(b0[2], b0[3]); w.z = cvt_pk_bf16(b1[0], b1[1]); w.w = cvt_pk_bf16(b1[2], b1[3]);
;                     *(u32x4*)(rowp + u.pn * 256 + 128 + wcol) = w;
;                 } else {
;                     f32x4 r0, r1;
;                     if (u.pn < 6) { r0 = a0 * b0; r1 = a1 * b1; }
;                     else {
; #pragma unroll
;                         for (int j = 0; j < 4; ++j) { r0[j] = a0[j] * __builtin_amdgcn_rcpf(1.0f + __expf(-b0[j])); r1[j] = a1[j] * __builtin_amdgcn_rcpf(1.0f + __expf(-b1[j])); }
;                     }
;                     u32x4 w; w.x = cvt_pk_bf16(r0[0], r0[1]); w.y = cvt_pk_bf16(r0[2], r0[3]); w.z = cvt_pk_bf16(r1[0], r1[1]); w.w = cvt_pk_bf16(r1[2], r1[3]);
;                     *(u32x4*)(rowp + (u.pn < 6 ? 512 + (u.pn - 2) * 128 : 1024 + (u.pn - 6) * 128) + wcol) = w;
.LBB0_150:
	v_fmamk_f32 v20, v149, 0x3a800000, v164
	v_rsq_f32_e32 v22, v20
	v_lshl_add_u64 v[20:21], v[38:39], 0, v[136:137]
	v_add_u32_e32 v23, 0xb0, v148
	global_store_dwordx4 v[20:21], v[16:19], off sc1
	v_pk_mul_f32 v[14:15], v[14:15], v[22:23] op_sel_hi:[1,0]
	v_pk_mul_f32 v[20:21], v[12:13], v[22:23] op_sel_hi:[1,0]
	v_mov_b64_e32 v[16:17], s[34:35]
	v_mad_i64_i32 v[16:17], s[12:13], v23, s64, v[16:17]
	v_pk_mul_f32 v[12:13], v[10:11], v[22:23] op_sel_hi:[1,0]
	v_pk_mul_f32 v[18:19], v[8:9], v[22:23] op_sel_hi:[1,0]
	v_pk_mul_f32 v[6:7], v[6:7], v[22:23] op_sel_hi:[1,0]
	v_pk_mul_f32 v[10:11], v[4:5], v[22:23] op_sel_hi:[1,0]
	v_pk_mul_f32 v[4:5], v[2:3], v[22:23] op_sel_hi:[1,0]
	v_pk_mul_f32 v[8:9], v[0:1], v[22:23] op_sel_hi:[1,0]
	s_and_b64 vcc, exec, s[0:1]
	s_mov_b64 s[0:1], -1
	s_cbranch_vccnz .LBB0_154
	s_cmp_lt_u32 s50, 6
	v_mov_b32_e32 v0, v10
	v_mov_b32_e32 v1, v11
	v_mov_b32_e32 v22, v6
	v_mov_b32_e32 v23, v7
	v_mov_b32_e32 v2, v8
	v_mov_b32_e32 v3, v9
	v_mov_b32_e32 v24, v4
	v_mov_b32_e32 v25, v5
	s_cbranch_scc1 .LBB0_153
	v_mul_f32_e32 v1, 0xbfb8aa3b, v8
	v_mul_f32_e32 v2, 0xbfb8aa3b, v11
	v_exp_f32_e32 v1, v1
	v_exp_f32_e32 v3, v2
	v_mul_f32_e32 v2, 0xbfb8aa3b, v9
	v_exp_f32_e32 v22, v2
	v_add_f32_e32 v1, 1.0, v1
	v_mul_f32_e32 v23, 0xbfb8aa3b, v4
	v_mul_f32_e32 v24, 0xbfb8aa3b, v7
	v_mul_f32_e32 v0, 0xbfb8aa3b, v10
	v_rcp_f32_e32 v2, v1
	v_add_f32_e32 v1, 1.0, v3
	v_add_f32_e32 v3, 1.0, v22
	v_mul_f32_e32 v22, 0xbfb8aa3b, v6
	v_exp_f32_e32 v23, v23
	v_exp_f32_e32 v25, v24
	v_mul_f32_e32 v24, 0xbfb8aa3b, v5
	v_exp_f32_e32 v0, v0
	v_exp_f32_e32 v22, v22
	v_exp_f32_e32 v26, v24
	v_add_f32_e32 v23, 1.0, v23
	v_add_f32_e32 v0, 1.0, v0
	v_add_f32_e32 v22, 1.0, v22
	v_rcp_f32_e32 v24, v23
	v_add_f32_e32 v23, 1.0, v25
	v_add_f32_e32 v25, 1.0, v26
	v_rcp_f32_e32 v0, v0
	v_rcp_f32_e32 v1, v1
	v_rcp_f32_e32 v3, v3
	v_rcp_f32_e32 v22, v22
	v_rcp_f32_e32 v23, v23
	v_rcp_f32_e32 v25, v25
